# hot k-loop heads (all role-split loops) aligned to 64-byte instruction-cache lines
# baseline (speedup 1.0000x reference)
; template <int N> DI void wait_vm() { asm volatile("s_waitcnt vmcnt(%0)" ::"n"(N) : "memory"); }
; DI void raw_barrier() { asm volatile("" ::: "memory"); __builtin_amdgcn_s_barrier(); asm volatile("" ::: "memory"); }
;     ...
;     auto issue_one = [&](int kt, int b, int i) {
;         const int row = lrow + 128 * i;
;         if ((NCH % 512 == 0) || (i < NCH / 512) || row < ROWS) {
;             const int kq = (kt + koff) & (KT - 1);
;             const char* ua = (const char*)A + (size_t)((DBG & 1) ? 0 : kq) * (BM * 64);
;             const char* ub = (const char*)Bt + (size_t)((DBG & 2) ? 0 : kq) * ((size_t)ldbk * 2);
;             const char* src;
;             if (BM % 128 == 0) src = (i < BM / 128) ? (ua + i * 8192 + loff) : (ub + (i * 128 - BM) * 64 + loff);
;             else if (i == 0) src = (lrow < BM) ? (ua + loff) : (ub + loff - BM * 64);
;             else src = ub + (i * 128 - BM) * 64 + loff;
;             __builtin_amdgcn_global_load_lds((const unsigned*)src, (unsigned*)(lds + b * BUF + i * 8192 + tid * 16), 16, 0, 0);
;         }
;     };
;     auto issue = [&](int kt, int b) {
; #pragma unroll
;         for (int i = 0; i < NIT; ++i) issue_one(kt, b, i);
;     ...
;     __syncthreads();
; #pragma unroll
;     for (int d = 0; d < D; ++d) issue(d, d);
;     int cb = 0, ib = D;
;     for (int kt = 0; kt < KT; ++kt) {
;         if (D > 1 && kt + D - 1 < KT) wait_vm<(D - 1) * NIT>(); else wait_vm<0>();
;         raw_barrier();
;         compute(cb, kt + D < KT, kt + D, ib);
.Lpo1_s0d_1:
	s_add_u32 s6, s6, 0x2000
	s_addc_u32 s7, s7, 0
	s_add_u32 m0, m0, 0x2000
	s_nop 0
	global_load_lds_dwordx4 v199, s[6:7]
	global_load_lds_dwordx4 v199, s[6:7] offset:1024
	s_add_u32 s6, s6, 0x2000
	s_addc_u32 s7, s7, 0
	s_add_u32 m0, m0, 0x2000
	s_nop 0
	global_load_lds_dwordx4 v199, s[6:7]
	global_load_lds_dwordx4 v199, s[6:7] offset:1024
	s_add_u32 s6, s6, 0x2000
	s_addc_u32 s7, s7, 0
	s_add_u32 m0, m0, 0x2000
	s_nop 0
	global_load_lds_dwordx4 v199, s[6:7]
	global_load_lds_dwordx4 v199, s[6:7] offset:1024
	s_add_u32 s6, s6, 0x2000
	s_addc_u32 s7, s7, 0
	s_add_u32 m0, m0, 0x2000
	s_nop 0
	global_load_lds_dwordx4 v199, s[6:7]
	global_load_lds_dwordx4 v199, s[6:7] offset:1024
	s_add_u32 s6, s6, 0x2000
	s_addc_u32 s7, s7, 0
	s_add_u32 m0, m0, 0x2000
	s_nop 0
	global_load_lds_dwordx4 v199, s[6:7]
	global_load_lds_dwordx4 v199, s[6:7] offset:1024
	s_add_u32 s6, s6, 0x2000
	s_addc_u32 s7, s7, 0
	s_add_u32 m0, m0, 0x2000
	s_nop 0
	global_load_lds_dwordx4 v199, s[6:7]
	global_load_lds_dwordx4 v199, s[6:7] offset:1024
	s_add_u32 s6, s6, 0x2000
	s_addc_u32 s7, s7, 0
	s_add_u32 m0, m0, 0x2000
	s_nop 0
	global_load_lds_dwordx4 v199, s[6:7]
	global_load_lds_dwordx4 v199, s[6:7] offset:1024
	s_add_u32 s6, s6, 0x2000
	s_addc_u32 s7, s7, 0
	s_lshr_b32 s46, s40, 1
	s_bitcmp1_b32 s9, 0
	s_cselect_b32 m0, 0x11000, 0
	s_add_u32 m0, m0, s46
	s_add_u32 m0, m0, 0x10000
	s_nop 0
	global_load_lds_dwordx4 v0, s[6:7]
	s_mov_b32 s9, 2
	s_waitcnt vmcnt(17)
	s_barrier
	v_add_u32_e32 v197, v140, v141
	v_add_u32_e32 v196, v140, v139
	ds_read_b128 v[146:149], v196
	ds_read_b128 v[154:157], v196 offset:1024
	ds_read_b128 v[182:185], v196 offset:2048
	ds_read_b128 v[142:145], v197 offset:4096
	ds_read_b128 v[150:153], v197 offset:5120
	ds_read_b128 v[158:161], v197 offset:6144
	ds_read_b128 v[162:165], v197 offset:7168
	ds_read_b128 v[166:169], v197 offset:8192
	ds_read_b128 v[170:173], v197 offset:9216
	ds_read_b128 v[174:177], v197 offset:10240
	ds_read_b128 v[178:181], v197 offset:11264
	ds_read_b128 v[186:189], v196 offset:3072
	.p2align 6

; template <int N> DI void wait_vm() { asm volatile("s_waitcnt vmcnt(%0)" ::"n"(N) : "memory"); }
; DI void raw_barrier() { asm volatile("" ::: "memory"); __builtin_amdgcn_s_barrier(); asm volatile("" ::: "memory"); }
;     ...
;     __syncthreads();
; #pragma unroll
;     for (int d = 0; d < D; ++d) issue(d, d);
;     int cb = 0, ib = D;
;     for (int kt = 0; kt < KT; ++kt) {
;         if (D > 1 && kt + D - 1 < KT) wait_vm<(D - 1) * NIT>(); else wait_vm<0>();
;         raw_barrier();
;         compute(cb, kt + D < KT, kt + D, ib);
.Lpo1_c_entry:
	v_subrev_u32_e32 v246, 0x100, v212
	v_readfirstlane_b32 s96, v130
	v_readfirstlane_b32 s97, v131
	v_readfirstlane_b32 s94, v0
	s_nop 3
	s_sub_u32 s96, s96, s94
	s_subb_u32 s97, s97, 0
	s_add_i32 s94, s33, 2
	v_lshrrev_b32_e32 v247, 5, v246
	v_add_u32_e32 v247, s94, v247
	v_and_b32_e32 v247, 31, v247
	v_and_b32_e32 v199, 31, v246
	v_lshlrev_b32_e32 v199, 7, v199
	v_lshl_or_b32 v247, v247, 12, v199
	s_nop 1
	global_load_dword v247, v247, s[96:97]
	s_mov_b32 s9, 2
	s_waitcnt vmcnt(1)
	s_barrier
	v_add_u32_e32 v197, v140, v141
	v_add_u32_e32 v196, v140, v139
	ds_read_b128 v[146:149], v196
	ds_read_b128 v[154:157], v196 offset:1024
	ds_read_b128 v[182:185], v196 offset:2048
	ds_read_b128 v[142:145], v197 offset:4096
	ds_read_b128 v[150:153], v197 offset:5120
	ds_read_b128 v[158:161], v197 offset:6144
	ds_read_b128 v[162:165], v197 offset:7168
	ds_read_b128 v[166:169], v197 offset:8192
	ds_read_b128 v[170:173], v197 offset:9216
	ds_read_b128 v[174:177], v197 offset:10240
	ds_read_b128 v[178:181], v197 offset:11264
	ds_read_b128 v[186:189], v196 offset:3072
	.p2align 6

; template <int N> DI void wait_vm() { asm volatile("s_waitcnt vmcnt(%0)" ::"n"(N) : "memory"); }
; DI void raw_barrier() { asm volatile("" ::: "memory"); __builtin_amdgcn_s_barrier(); asm volatile("" ::: "memory"); }
;     ...
;     auto issue_one = [&](int kt, int b, int i) {
;         const int row = lrow + 128 * i;
;         if ((NCH % 512 == 0) || (i < NCH / 512) || row < ROWS) {
;             const int kq = (kt + koff) & (KT - 1);
;             const char* ua = (const char*)A + (size_t)((DBG & 1) ? 0 : kq) * (BM * 64);
;             const char* ub = (const char*)Bt + (size_t)((DBG & 2) ? 0 : kq) * ((size_t)ldbk * 2);
;             const char* src;
;             if (BM % 128 == 0) src = (i < BM / 128) ? (ua + i * 8192 + loff) : (ub + (i * 128 - BM) * 64 + loff);
;             else if (i == 0) src = (lrow < BM) ? (ua + loff) : (ub + loff - BM * 64);
;             else src = ub + (i * 128 - BM) * 64 + loff;
;             __builtin_amdgcn_global_load_lds((const unsigned*)src, (unsigned*)(lds + b * BUF + i * 8192 + tid * 16), 16, 0, 0);
;         }
;     };
;     auto issue = [&](int kt, int b) {
; #pragma unroll
;         for (int i = 0; i < NIT; ++i) issue_one(kt, b, i);
;     ...
;     __syncthreads();
; #pragma unroll
;     for (int d = 0; d < D; ++d) issue(d, d);
;     int cb = 0, ib = D;
;     for (int kt = 0; kt < KT; ++kt) {
;         if (D > 1 && kt + D - 1 < KT) wait_vm<(D - 1) * NIT>(); else wait_vm<0>();
;         raw_barrier();
;         compute(cb, kt + D < KT, kt + D, ib);
.Lpo2_s0d_1:
	s_add_u32 s8, s8, 0x2000
	s_addc_u32 s9, s9, 0
	s_add_u32 m0, m0, 0x2000
	s_nop 0
	global_load_lds_dwordx4 v199, s[8:9]
	global_load_lds_dwordx4 v199, s[8:9] offset:1024
	s_add_u32 s8, s8, 0x2000
	s_addc_u32 s9, s9, 0
	s_add_u32 m0, m0, 0x2000
	s_nop 0
	global_load_lds_dwordx4 v199, s[8:9]
	global_load_lds_dwordx4 v199, s[8:9] offset:1024
	s_add_u32 s8, s8, 0x2000
	s_addc_u32 s9, s9, 0
	s_add_u32 m0, m0, 0x2000
	s_nop 0
	global_load_lds_dwordx4 v199, s[8:9]
	global_load_lds_dwordx4 v199, s[8:9] offset:1024
	s_add_u32 s8, s8, 0x2000
	s_addc_u32 s9, s9, 0
	s_add_u32 m0, m0, 0x2000
	s_nop 0
	global_load_lds_dwordx4 v199, s[8:9]
	global_load_lds_dwordx4 v199, s[8:9] offset:1024
	s_add_u32 s8, s8, 0x2000
	s_addc_u32 s9, s9, 0
	s_add_u32 m0, m0, 0x2000
	s_nop 0
	global_load_lds_dwordx4 v199, s[8:9]
	global_load_lds_dwordx4 v199, s[8:9] offset:1024
	s_add_u32 s8, s8, 0x2000
	s_addc_u32 s9, s9, 0
	s_add_u32 m0, m0, 0x2000
	s_nop 0
	global_load_lds_dwordx4 v199, s[8:9]
	global_load_lds_dwordx4 v199, s[8:9] offset:1024
	s_add_u32 s8, s8, 0x2000
	s_addc_u32 s9, s9, 0
	s_add_u32 m0, m0, 0x2000
	s_nop 0
	global_load_lds_dwordx4 v199, s[8:9]
	global_load_lds_dwordx4 v199, s[8:9] offset:1024
	s_add_u32 s8, s8, 0x2000
	s_addc_u32 s9, s9, 0
	s_lshr_b32 s46, s40, 1
	s_bitcmp1_b32 s29, 0
	s_cselect_b32 m0, 0x11000, 0
	s_add_u32 m0, m0, s46
	s_add_u32 m0, m0, 0x10000
	s_nop 0
	global_load_lds_dwordx4 v0, s[8:9]
	s_mov_b32 s29, 2
	s_waitcnt vmcnt(17)
	s_barrier
	v_add_u32_e32 v197, v140, v141
	v_add_u32_e32 v196, v140, v139
	ds_read_b128 v[146:149], v196
	ds_read_b128 v[154:157], v196 offset:1024
	ds_read_b128 v[182:185], v196 offset:2048
	ds_read_b128 v[142:145], v197 offset:4096
	ds_read_b128 v[150:153], v197 offset:5120
	ds_read_b128 v[158:161], v197 offset:6144
	ds_read_b128 v[162:165], v197 offset:7168
	ds_read_b128 v[166:169], v197 offset:8192
	ds_read_b128 v[170:173], v197 offset:9216
	ds_read_b128 v[174:177], v197 offset:10240
	ds_read_b128 v[178:181], v197 offset:11264
	ds_read_b128 v[186:189], v196 offset:3072
	.p2align 6

; template <int N> DI void wait_vm() { asm volatile("s_waitcnt vmcnt(%0)" ::"n"(N) : "memory"); }
; DI void raw_barrier() { asm volatile("" ::: "memory"); __builtin_amdgcn_s_barrier(); asm volatile("" ::: "memory"); }
;     ...
;     __syncthreads();
; #pragma unroll
;     for (int d = 0; d < D; ++d) issue(d, d);
;     int cb = 0, ib = D;
;     for (int kt = 0; kt < KT; ++kt) {
;         if (D > 1 && kt + D - 1 < KT) wait_vm<(D - 1) * NIT>(); else wait_vm<0>();
;         raw_barrier();
;         compute(cb, kt + D < KT, kt + D, ib);
.Lpo2_c_entry:
	v_subrev_u32_e32 v246, 0x100, v212
	v_readfirstlane_b32 s96, v130
	v_readfirstlane_b32 s97, v131
	v_readfirstlane_b32 s94, v0
	s_nop 3
	s_sub_u32 s96, s96, s94
	s_subb_u32 s97, s97, 0
	s_add_i32 s94, s33, 2
	v_lshrrev_b32_e32 v247, 5, v246
	v_add_u32_e32 v247, s94, v247
	v_and_b32_e32 v247, 31, v247
	v_and_b32_e32 v199, 31, v246
	v_lshlrev_b32_e32 v199, 7, v199
	v_lshl_or_b32 v247, v247, 12, v199
	s_nop 1
	global_load_dword v247, v247, s[96:97]
	s_mov_b32 s29, 2
	s_waitcnt vmcnt(1)
	s_barrier
	v_add_u32_e32 v197, v140, v141
	v_add_u32_e32 v196, v140, v139
	ds_read_b128 v[146:149], v196
	ds_read_b128 v[154:157], v196 offset:1024
	ds_read_b128 v[182:185], v196 offset:2048
	ds_read_b128 v[142:145], v197 offset:4096
	ds_read_b128 v[150:153], v197 offset:5120
	ds_read_b128 v[158:161], v197 offset:6144
	ds_read_b128 v[162:165], v197 offset:7168
	ds_read_b128 v[166:169], v197 offset:8192
	ds_read_b128 v[170:173], v197 offset:9216
	ds_read_b128 v[174:177], v197 offset:10240
	ds_read_b128 v[178:181], v197 offset:11264
	ds_read_b128 v[186:189], v196 offset:3072
	.p2align 6

; DI int opaque_tid() { int t = threadIdx.x; asm volatile("" : "+v"(t)); return t; }
;     constexpr int WM = BM / WR, WN = BN / WC, MT = WM / 16, NT = WN / 16, ROWS = BM + BN, NCH = ROWS * 4, NIT = (NCH + 511) / 512, BUF = ROWS * 64, KT = 32;
;     constexpr int NTS = NT / NSEG, D = NST - 1;
;     static_assert(D == 1 || (NCH % 512 == 0), "deep ring needs a uniform per-thread load count");
;     const int tid = opaque_tid(), lane = tid & 63, wid = tid >> 6, wr = wid / WC, wc = wid % WC, l15 = lane & 15, quad = lane >> 4;
;     const int lrow = tid >> 2, lc = tid & 3;
;     const int lcg = lc ^ ((0 - (tid >> 4)) & 3);
;     const int rsw = (quad ^ ((0 - (l15 >> 2)) & 3)) << 4;
; #pragma unroll
;     for (int mt = 0; mt < MT; ++mt)
; #pragma unroll
;         for (int nt = 0; nt < NT; ++nt) acc[mt][nt] = (f32x4){0.f, 0.f, 0.f, 0.f};
;     const unsigned loff = (unsigned)(lrow * 64 + lcg * 16);
;     const int koff = (int)((blockIdx.x >> 3) + (blockIdx.x & 7) * 4) & (KT - 1);
;     auto issue_one = [&](int kt, int b, int i) {
;         const int row = lrow + 128 * i;
;         if ((NCH % 512 == 0) || (i < NCH / 512) || row < ROWS) {
;             const int kq = (kt + koff) & (KT - 1);
;             const char* ua = (const char*)A + (size_t)((DBG & 1) ? 0 : kq) * (BM * 64);
;             const char* ub = (const char*)Bt + (size_t)((DBG & 2) ? 0 : kq) * ((size_t)ldbk * 2);
;             const char* src;
;             if (BM % 128 == 0) src = (i < BM / 128) ? (ua + i * 8192 + loff) : (ub + (i * 128 - BM) * 64 + loff);
;             else if (i == 0) src = (lrow < BM) ? (ua + loff) : (ub + loff - BM * 64);
;             else src = ub + (i * 128 - BM) * 64 + loff;
;             __builtin_amdgcn_global_load_lds((const unsigned*)src, (unsigned*)(lds + b * BUF + i * 8192 + tid * 16), 16, 0, 0);
;         }
;     };
;     auto issue = [&](int kt, int b) {
; #pragma unroll
;         for (int i = 0; i < NIT; ++i) issue_one(kt, b, i);
;     ...
;     __syncthreads();
; #pragma unroll
;     for (int d = 0; d < D; ++d) issue(d, d);
.LBB0_740:
	s_and_b64 vcc, exec, s[6:7]
	s_cbranch_vccz .LBB0_824
	v_mov_b32_e32 v137, v212
	v_mov_b32_e32 v4, v212
	s_lshl_b32 s0, s40, 5
	v_ashrrev_i32_e32 v5, 6, v4
	v_lshrrev_b32_e32 v0, 30, v5
	v_add_u32_e32 v0, v5, v0
	v_ashrrev_i32_e32 v6, 2, v0
	v_lshrrev_b32_e32 v0, 4, v4
	s_or_b32 s8, s0, s73
	v_sub_u32_e32 v0, 0, v0
	v_lshlrev_b32_e32 v2, 2, v4
	s_lshl_b32 s13, s8, 7
	s_lshl_b32 s0, s8, 18
	v_readlane_b32 s1, v243, 56
	v_and_b32_e32 v2, 48, v2
	v_xor_b32_e32 v0, v4, v0
	v_lshlrev_b32_e32 v8, 4, v4
	s_add_u32 s10, s1, s0
	v_readlane_b32 s0, v243, 40
	v_sub_u32_e32 v7, 0, v2
	v_and_b32_e32 v2, 0xffffffc0, v8
	v_lshlrev_b32_e32 v0, 4, v0
	s_addc_u32 s11, s0, 0
	v_and_or_b32 v0, v0, 48, v2
	v_lshl_add_u64 v[130:131], s[10:11], 0, v[0:1]
	v_readlane_b32 s10, v243, 25
	v_add_u32_e32 v134, 0, v8
	v_readlane_b32 s11, v243, 26
	v_readfirstlane_b32 s7, v134
	s_mov_b32 m0, s7
	v_lshl_add_u64 v[2:3], v[130:131], 0, s[10:11]
	s_barrier
	global_load_lds_dwordx4 v[2:3], off
	v_add_u32_e32 v2, 0x2000, v134
	v_readlane_b32 s10, v242, 7
	v_readfirstlane_b32 s7, v2
	s_mov_b32 m0, s7
	v_readlane_b32 s11, v242, 8
	v_add_u32_e32 v2, 0x4000, v134
	v_add_u32_e32 v9, 0xa000, v134
	v_readfirstlane_b32 s7, v2
	v_add_u32_e32 v2, 0x6000, v134
	s_add_i32 s12, 0, 0x10000
	global_load_lds_dwordx4 v0, s[10:11]
	v_readlane_b32 s10, v242, 3
	s_mov_b32 m0, s7
	v_readlane_b32 s11, v242, 4
	v_readfirstlane_b32 s7, v2
	v_add_u32_e32 v2, 0x8000, v134
	s_mov_b32 s1, 2
	s_mov_b32 s0, 4
	s_mov_b32 s6, 0
	global_load_lds_dwordx4 v0, s[10:11]
	v_readlane_b32 s10, v242, 5
	s_mov_b32 m0, s7
	v_readlane_b32 s11, v242, 6
	v_readfirstlane_b32 s7, v2
	v_lshl_add_u64 v[132:133], s[50:51], 0, v[0:1]
	s_nop 2
	global_load_lds_dwordx4 v0, s[10:11]
	v_readlane_b32 s10, v242, 9
	s_mov_b32 m0, s7
	v_readlane_b32 s11, v242, 10
	v_readfirstlane_b32 s7, v9
	s_nop 3
	global_load_lds_dwordx4 v0, s[10:11]
	v_readlane_b32 s10, v243, 5
	v_readlane_b32 s11, v243, 6
	s_mov_b32 m0, s7
	s_nop 0
	v_lshl_add_u64 v[2:3], v[130:131], 0, s[10:11]
	global_load_lds_dwordx4 v[2:3], off
	v_add_u32_e32 v2, 0xc000, v134
	v_readlane_b32 s10, v242, 15
	v_readfirstlane_b32 s7, v2
	s_mov_b32 m0, s7
	v_readlane_b32 s11, v242, 16
	v_add_u32_e32 v2, 0xe000, v134
	v_bitop3_b32 v3, v4, 48, v7 bitop3:0x48
	v_readfirstlane_b32 s7, v2
	v_add_u32_e32 v2, s12, v8
	v_add_u32_e32 v135, 0, v3
	global_load_lds_dwordx4 v0, s[10:11]
	v_readlane_b32 s10, v242, 11
	s_mov_b32 m0, s7
	v_readlane_b32 s11, v242, 12
	v_readfirstlane_b32 s7, v2
	v_lshlrev_b32_e32 v3, 6, v4
	v_and_b32_e32 v3, 0x3c0, v3
	v_lshl_or_b32 v136, v6, 12, v3
	s_nop 0
	global_load_lds_dwordx4 v0, s[10:11]
	s_mov_b32 m0, s7
	v_readlane_b32 s10, v242, 13
	v_readlane_b32 s7, v243, 31
	v_readlane_b32 s11, v242, 14
	s_nop 0
	v_add_u32_e32 v2, s7, v8
	s_nop 0
	v_readfirstlane_b32 s7, v2
	v_mul_i32_i24_e32 v2, 4, v6
	global_load_lds_dwordx4 v0, s[10:11]
	v_readlane_b32 s10, v242, 17
	s_mov_b32 m0, s7
	v_readlane_b32 s11, v242, 18
	v_sub_u32_e32 v2, v5, v2
	v_lshl_or_b32 v138, v2, 13, v3
	v_mov_b32_e32 v2, 0
	v_readlane_b32 s7, v243, 24
	v_mov_b32_e32 v3, v2
	global_load_lds_dwordx4 v0, s[10:11]
	v_mov_b32_e32 v4, v2
	v_mov_b32_e32 v5, v2
	v_mov_b32_e32 v6, v2
	v_mov_b32_e32 v7, v2
	v_mov_b32_e32 v8, v2
	v_mov_b32_e32 v9, v2
	v_mov_b32_e32 v10, v2
	v_mov_b32_e32 v11, v2
	v_mov_b32_e32 v12, v2
	v_mov_b32_e32 v13, v2
	v_mov_b32_e32 v14, v2
	v_mov_b32_e32 v15, v2
	v_mov_b32_e32 v16, v2
	v_mov_b32_e32 v17, v2
	v_mov_b32_e32 v18, v2
	v_mov_b32_e32 v19, v2
	v_mov_b32_e32 v20, v2
	v_mov_b32_e32 v21, v2
	v_mov_b32_e32 v22, v2
	v_mov_b32_e32 v23, v2
	v_mov_b32_e32 v24, v2
	v_mov_b32_e32 v25, v2
	v_mov_b32_e32 v26, v2
	v_mov_b32_e32 v27, v2
	v_mov_b32_e32 v28, v2
	v_mov_b32_e32 v29, v2
	v_mov_b32_e32 v30, v2
	v_mov_b32_e32 v31, v2
	v_mov_b32_e32 v32, v2
	v_mov_b32_e32 v33, v2
	v_mov_b32_e32 v34, v2
	v_mov_b32_e32 v35, v2
	v_mov_b32_e32 v36, v2
	v_mov_b32_e32 v37, v2
	v_mov_b32_e32 v38, v2
	v_mov_b32_e32 v39, v2
	v_mov_b32_e32 v40, v2
	v_mov_b32_e32 v41, v2
	v_mov_b32_e32 v42, v2
	v_mov_b32_e32 v43, v2
	v_mov_b32_e32 v44, v2
	v_mov_b32_e32 v45, v2
	v_mov_b32_e32 v46, v2
	v_mov_b32_e32 v47, v2
	v_mov_b32_e32 v48, v2
	v_mov_b32_e32 v49, v2
	v_mov_b32_e32 v50, v2
	v_mov_b32_e32 v51, v2
	v_mov_b32_e32 v52, v2
	v_mov_b32_e32 v53, v2
	v_mov_b32_e32 v54, v2
	v_mov_b32_e32 v55, v2
	v_mov_b32_e32 v56, v2
	v_mov_b32_e32 v57, v2
	v_mov_b32_e32 v58, v2
	v_mov_b32_e32 v59, v2
	v_mov_b32_e32 v60, v2
	v_mov_b32_e32 v61, v2
	v_mov_b32_e32 v62, v2
	v_mov_b32_e32 v63, v2
	v_mov_b32_e32 v64, v2
	v_mov_b32_e32 v65, v2
	v_mov_b32_e32 v66, v2
	v_mov_b32_e32 v67, v2
	v_mov_b32_e32 v68, v2
	v_mov_b32_e32 v69, v2
	v_mov_b32_e32 v70, v2
	v_mov_b32_e32 v71, v2
	v_mov_b32_e32 v72, v2
	v_mov_b32_e32 v73, v2
	v_mov_b32_e32 v74, v2
	v_mov_b32_e32 v75, v2
	v_mov_b32_e32 v76, v2
	v_mov_b32_e32 v77, v2
	v_mov_b32_e32 v78, v2
	v_mov_b32_e32 v79, v2
	v_mov_b32_e32 v80, v2
	v_mov_b32_e32 v81, v2
	v_mov_b32_e32 v82, v2
	v_mov_b32_e32 v83, v2
	v_mov_b32_e32 v84, v2
	v_mov_b32_e32 v85, v2
	v_mov_b32_e32 v86, v2
	v_mov_b32_e32 v87, v2
	v_mov_b32_e32 v88, v2
	v_mov_b32_e32 v89, v2
	v_mov_b32_e32 v90, v2
	v_mov_b32_e32 v91, v2
	v_mov_b32_e32 v92, v2
	v_mov_b32_e32 v93, v2
	v_mov_b32_e32 v94, v2
	v_mov_b32_e32 v95, v2
	v_mov_b32_e32 v96, v2
	v_mov_b32_e32 v97, v2
	v_mov_b32_e32 v98, v2
	v_mov_b32_e32 v99, v2
	v_mov_b32_e32 v100, v2
	v_mov_b32_e32 v101, v2
	v_mov_b32_e32 v102, v2
	v_mov_b32_e32 v103, v2
	v_mov_b32_e32 v104, v2
	v_mov_b32_e32 v105, v2
	v_mov_b32_e32 v106, v2
	v_mov_b32_e32 v107, v2
	v_mov_b32_e32 v108, v2
	v_mov_b32_e32 v109, v2
	v_mov_b32_e32 v110, v2
	v_mov_b32_e32 v111, v2
	v_mov_b32_e32 v112, v2
	v_mov_b32_e32 v113, v2
	v_mov_b32_e32 v114, v2
	v_mov_b32_e32 v115, v2
	s_waitcnt lgkmcnt(0)
	v_mov_b32_e32 v116, v2
	v_mov_b32_e32 v117, v2
	v_mov_b32_e32 v118, v2
	v_mov_b32_e32 v119, v2
	v_mov_b32_e32 v120, v2
	v_mov_b32_e32 v121, v2
	v_mov_b32_e32 v122, v2
	v_mov_b32_e32 v123, v2
	v_mov_b32_e32 v124, v2
	v_mov_b32_e32 v125, v2
	v_mov_b32_e32 v126, v2
	v_mov_b32_e32 v127, v2
	v_mov_b32_e32 v128, v2
	v_mov_b32_e32 v129, v2
	v_readfirstlane_b32 s9, v212
	s_nop 3
	s_cmp_lt_u32 s9, 0x100
	s_cbranch_scc0 .Lpx_c_entry
; template <int N> DI void wait_vm() { asm volatile("s_waitcnt vmcnt(%0)" ::"n"(N) : "memory"); }
; DI void raw_barrier() { asm volatile("" ::: "memory"); __builtin_amdgcn_s_barrier(); asm volatile("" ::: "memory"); }
;     ...
;     auto issue_one = [&](int kt, int b, int i) {
;         const int row = lrow + 128 * i;
;         if ((NCH % 512 == 0) || (i < NCH / 512) || row < ROWS) {
;             const int kq = (kt + koff) & (KT - 1);
;             const char* ua = (const char*)A + (size_t)((DBG & 1) ? 0 : kq) * (BM * 64);
;             const char* ub = (const char*)Bt + (size_t)((DBG & 2) ? 0 : kq) * ((size_t)ldbk * 2);
;             const char* src;
;             if (BM % 128 == 0) src = (i < BM / 128) ? (ua + i * 8192 + loff) : (ub + (i * 128 - BM) * 64 + loff);
;             else if (i == 0) src = (lrow < BM) ? (ua + loff) : (ub + loff - BM * 64);
;             else src = ub + (i * 128 - BM) * 64 + loff;
;             __builtin_amdgcn_global_load_lds((const unsigned*)src, (unsigned*)(lds + b * BUF + i * 8192 + tid * 16), 16, 0, 0);
;         }
;     };
;     auto issue = [&](int kt, int b) {
; #pragma unroll
;         for (int i = 0; i < NIT; ++i) issue_one(kt, b, i);
;     };
;     auto compute = [&](int cb, bool do_issue, int ikt, int ib) {
;         const char* base = lds + cb * BUF;
;         bf16x8 af[MT], bfr[NT];
; #pragma unroll
;         for (int nt = 0; nt < NT; ++nt) {
;             const int br = BM + (nt / NTS) * (BN / NSEG) + wc * (NTS * 16) + (nt % NTS) * 16;
;             bfr[nt] = *(const bf16x8*)(base + (br + l15) * 64 + rsw);
;         }
; #pragma unroll
;         for (int mt = 0; mt < MT; ++mt) af[mt] = *(const bf16x8*)(base + (wr * WM + mt * 16 + l15) * 64 + rsw);
;     ...
;     __syncthreads();
; #pragma unroll
;     for (int d = 0; d < D; ++d) issue(d, d);
;     int cb = 0, ib = D;
;     for (int kt = 0; kt < KT; ++kt) {
;         if (D > 1 && kt + D - 1 < KT) wait_vm<(D - 1) * NIT>(); else wait_vm<0>();
;         raw_barrier();
;         compute(cb, kt + D < KT, kt + D, ib);
	s_lshl_b32 s7, s9, 5
	s_lshl_b32 s40, s9, 4
	v_add_u32_e32 v227, s40, v0
	v_readfirstlane_b32 s10, v130
	v_readfirstlane_b32 s11, v131
	v_readfirstlane_b32 s40, v0
	s_nop 3
	s_sub_u32 vcc_lo, s10, s40
	s_subb_u32 vcc_hi, s11, 0
	s_mul_i32 s10, s1, 0xa000
	s_add_u32 s10, s10, s7
	s_mov_b32 m0, s10
	s_add_i32 s40, s59, s0
	s_and_b32 s40, s40, 62
	s_lshl_b32 s10, s40, 12
	s_add_u32 s10, vcc_lo, s10
	s_addc_u32 s11, vcc_hi, 0
	s_mul_i32 s40, s40, 0x14000
	global_load_lds_dwordx4 v227, s[10:11]
	global_load_lds_dwordx4 v227, s[10:11] offset:1024
	s_add_u32 s10, s50, s40
	s_addc_u32 s11, s51, 0
	s_add_u32 m0, m0, 0x2000
	s_nop 0
	global_load_lds_dwordx4 v227, s[10:11]
	global_load_lds_dwordx4 v227, s[10:11] offset:1024
	s_add_u32 s10, s10, 0x2000
	s_addc_u32 s11, s11, 0
	s_add_u32 m0, m0, 0x2000
	s_nop 0
	global_load_lds_dwordx4 v227, s[10:11]
	global_load_lds_dwordx4 v227, s[10:11] offset:1024
	s_add_u32 s10, s10, 0x2000
	s_addc_u32 s11, s11, 0
	s_add_u32 m0, m0, 0x2000
	s_nop 0
	global_load_lds_dwordx4 v227, s[10:11]
	global_load_lds_dwordx4 v227, s[10:11] offset:1024
	s_add_u32 s10, s10, 0x2000
	s_addc_u32 s11, s11, 0
	s_add_u32 m0, m0, 0x2000
	s_nop 0
	global_load_lds_dwordx4 v227, s[10:11]
	global_load_lds_dwordx4 v227, s[10:11] offset:1024
	s_add_i32 s0, s0, 2
	s_mov_b32 s1, 0
	s_mov_b32 s6, 1
	s_waitcnt vmcnt(15)
	s_barrier
	v_add_u32_e32 v225, v135, v138
	v_add_u32_e32 v224, v135, v136
	ds_read_b128 v[144:147], v224
	ds_read_b128 v[152:155], v224 offset:1024
	ds_read_b128 v[180:183], v224 offset:2048
	ds_read_b128 v[140:143], v225 offset:8192
	ds_read_b128 v[148:151], v225 offset:9216
	ds_read_b128 v[156:159], v225 offset:10240
	ds_read_b128 v[160:163], v225 offset:11264
	ds_read_b128 v[164:167], v225 offset:12288
	ds_read_b128 v[168:171], v225 offset:13312
	ds_read_b128 v[172:175], v225 offset:14336
	ds_read_b128 v[176:179], v225 offset:15360
	ds_read_b128 v[184:187], v224 offset:3072
	.p2align 6

; template <int N> DI void wait_vm() { asm volatile("s_waitcnt vmcnt(%0)" ::"n"(N) : "memory"); }
; DI void raw_barrier() { asm volatile("" ::: "memory"); __builtin_amdgcn_s_barrier(); asm volatile("" ::: "memory"); }
;     ...
;         for (int nt = 0; nt < NT; ++nt) {
;             const int br = BM + (nt / NTS) * (BN / NSEG) + wc * (NTS * 16) + (nt % NTS) * 16;
;             bfr[nt] = *(const bf16x8*)(base + (br + l15) * 64 + rsw);
;         }
; #pragma unroll
;         for (int mt = 0; mt < MT; ++mt) af[mt] = *(const bf16x8*)(base + (wr * WM + mt * 16 + l15) * 64 + rsw);
;     ...
;     for (int kt = 0; kt < KT; ++kt) {
;         if (D > 1 && kt + D - 1 < KT) wait_vm<(D - 1) * NIT>(); else wait_vm<0>();
;         raw_barrier();
;         compute(cb, kt + D < KT, kt + D, ib);
.Lpx_c_entry:
	s_add_i32 s0, s0, 2
	s_mov_b32 s6, 1
	s_waitcnt vmcnt(5)
	s_barrier
	v_add_u32_e32 v225, v135, v138
	v_add_u32_e32 v224, v135, v136
	ds_read_b128 v[144:147], v224
	ds_read_b128 v[152:155], v224 offset:1024
	ds_read_b128 v[180:183], v224 offset:2048
	ds_read_b128 v[140:143], v225 offset:8192
	ds_read_b128 v[148:151], v225 offset:9216
	ds_read_b128 v[156:159], v225 offset:10240
	ds_read_b128 v[160:163], v225 offset:11264
	ds_read_b128 v[164:167], v225 offset:12288
	ds_read_b128 v[168:171], v225 offset:13312
	ds_read_b128 v[172:175], v225 offset:14336
	ds_read_b128 v[176:179], v225 offset:15360
	ds_read_b128 v[184:187], v224 offset:3072
	.p2align 6

;     ...
;     __syncthreads();
; #pragma unroll
;     for (int d = 0; d < D; ++d) issue(d, d);
; DI void unit_A(const Params& p, char* lds, int l, int chunk, int h) {
;     ...
;     char* WL = lds + 98304;
;     __syncthreads();
;     {
;         const bf16_t* W = WS_PTR(const bf16_t, OFF_WSP) + (size_t)(l * 4 + h) * 16384;
; #pragma unroll
;         for (int i = 0; i < 4; ++i) {
;             const int piece = wid + 8 * i, row = piece * 4 + (lane >> 4), lc = (lane & 15) ^ (row & 15);
;             __builtin_amdgcn_global_load_lds((const unsigned*)(W + row * 128 + lc * 8), (unsigned*)(WL + piece * 1024 + lane * 16), 16, 0, 0);
;         }
;     }
.LBB0_825:
	s_andn2_b64 vcc, exec, s[6:7]
	s_cbranch_vccnz .LBB0_858
	s_ashr_i32 s1, s79, 8
	v_readlane_b32 s6, v242, 23
	s_add_i32 s6, s1, s6
	s_ashr_i32 s7, s6, 31
	s_and_b32 s0, s2, 0xff
	s_lshl_b64 s[8:9], s[6:7], 15
	v_readlane_b32 s7, v244, 40
	v_mov_b32_e32 v191, v212
	s_add_u32 s8, s7, s8
	v_readlane_b32 s7, v244, 41
	s_addc_u32 s9, s7, s9
	v_and_b32_e32 v0, 63, v191
	v_ashrrev_i32_e32 v4, 6, v191
	s_add_i32 s10, 0, 0x18000
	v_bfe_u32 v190, v191, 4, 2
	v_lshl_add_u32 v5, v0, 4, s10
	v_lshlrev_b32_e32 v0, 2, v4
	v_or_b32_e32 v2, v0, v190
	v_bitop3_b32 v0, v0, v191, v190 bitop3:0x36
	v_lshlrev_b32_e32 v2, 7, v2
	v_ashrrev_i32_e32 v3, 31, v2
	v_lshlrev_b32_e32 v0, 4, v0
	v_lshl_add_u64 v[2:3], v[2:3], 1, s[8:9]
	v_and_b32_e32 v0, 0xf0, v0
	v_lshl_add_u64 v[2:3], v[2:3], 0, v[0:1]
	v_lshl_add_u32 v0, v4, 10, v5
	v_add_u32_e32 v6, 8, v4
	v_readfirstlane_b32 s12, v0
	s_mov_b32 m0, s12
	v_lshlrev_b32_e32 v0, 2, v6
	s_barrier
	global_load_lds_dwordx4 v[2:3], off
	v_or_b32_e32 v2, v0, v190
	v_bitop3_b32 v0, v0, v191, v190 bitop3:0x36
	v_lshlrev_b32_e32 v2, 7, v2
	v_ashrrev_i32_e32 v3, 31, v2
	v_lshlrev_b32_e32 v0, 4, v0
	v_lshl_add_u64 v[2:3], v[2:3], 1, s[8:9]
	v_and_b32_e32 v0, 0xf0, v0
	v_lshl_add_u64 v[2:3], v[2:3], 0, v[0:1]
	v_lshl_add_u32 v0, v6, 10, v5
	v_add_u32_e32 v6, 16, v4
	v_readfirstlane_b32 s12, v0
	s_mov_b32 m0, s12
	v_lshlrev_b32_e32 v0, 2, v6
	global_load_lds_dwordx4 v[2:3], off
	v_or_b32_e32 v2, v0, v190
	v_bitop3_b32 v0, v0, v191, v190 bitop3:0x36
	v_lshlrev_b32_e32 v2, 7, v2
	v_ashrrev_i32_e32 v3, 31, v2
	v_lshlrev_b32_e32 v0, 4, v0
	v_lshl_add_u64 v[2:3], v[2:3], 1, s[8:9]
	v_and_b32_e32 v0, 0xf0, v0
	v_lshl_add_u64 v[2:3], v[2:3], 0, v[0:1]
	v_lshl_add_u32 v0, v6, 10, v5
	v_add_u32_e32 v4, 24, v4
	v_readfirstlane_b32 s12, v0
	s_mov_b32 m0, s12
	v_lshlrev_b32_e32 v0, 2, v4
	global_load_lds_dwordx4 v[2:3], off
	v_or_b32_e32 v2, v0, v190
	v_bitop3_b32 v0, v0, v191, v190 bitop3:0x36
	v_lshlrev_b32_e32 v2, 7, v2
	v_ashrrev_i32_e32 v3, 31, v2
	v_lshlrev_b32_e32 v0, 4, v0
	v_lshl_add_u64 v[2:3], v[2:3], 1, s[8:9]
	v_and_b32_e32 v0, 0xf0, v0
	v_lshl_add_u64 v[2:3], v[2:3], 0, v[0:1]
	v_lshl_add_u32 v0, v4, 10, v5
	v_mov_b32_e32 v6, v212
	v_readfirstlane_b32 s8, v0
	s_mov_b32 m0, s8
	s_lshl_b32 s8, s0, 18
	global_load_lds_dwordx4 v[2:3], off
	v_readlane_b32 s9, v243, 56
	v_ashrrev_i32_e32 v7, 6, v6
	v_lshrrev_b32_e32 v0, 30, v7
	v_add_u32_e32 v0, v7, v0
	v_ashrrev_i32_e32 v8, 2, v0
	v_lshrrev_b32_e32 v0, 4, v6
	v_sub_u32_e32 v0, 0, v0
	v_lshlrev_b32_e32 v2, 2, v6
	v_and_b32_e32 v2, 48, v2
	v_xor_b32_e32 v0, v6, v0
	v_lshlrev_b32_e32 v4, 4, v6
	s_add_u32 s14, s9, s8
	v_readlane_b32 s8, v243, 40
	v_sub_u32_e32 v9, 0, v2
	v_and_b32_e32 v2, 0xffffffc0, v4
	v_lshlrev_b32_e32 v0, 4, v0
	s_addc_u32 s15, s8, 0
	s_mul_i32 s8, s1, 0x6000
	v_readlane_b32 s12, v242, 24
	v_and_or_b32 v0, v0, 48, v2
	v_add_u32_e32 v102, 0, v4
	s_mul_hi_i32 s9, s1, 0x6000
	s_add_u32 s8, s12, s8
	v_readlane_b32 s12, v242, 25
	v_lshl_add_u64 v[98:99], s[14:15], 0, v[0:1]
	v_readlane_b32 s14, v243, 25
	v_readfirstlane_b32 s13, v102
	s_addc_u32 s9, s12, s9
	v_readlane_b32 s15, v243, 26
	s_mov_b32 m0, s13
	v_readlane_b32 s13, v243, 4
	v_lshl_add_u64 v[2:3], v[98:99], 0, s[14:15]
	s_add_u32 s14, s8, s13
	v_add_u32_e32 v4, 0x2000, v102
	s_addc_u32 s15, s9, 0
	v_readfirstlane_b32 s13, v4
	v_add_u32_e32 v10, 0x4000, v102
	s_waitcnt vmcnt(0) lgkmcnt(0)
	s_barrier
; template <int N> DI void wait_vm() { asm volatile("s_waitcnt vmcnt(%0)" ::"n"(N) : "memory"); }
; DI void raw_barrier() { asm volatile("" ::: "memory"); __builtin_amdgcn_s_barrier(); asm volatile("" ::: "memory"); }
;     ...
; #pragma unroll
;     for (int mt = 0; mt < MT; ++mt)
; #pragma unroll
;         for (int nt = 0; nt < NT; ++nt) acc[mt][nt] = (f32x4){0.f, 0.f, 0.f, 0.f};
;     const unsigned loff = (unsigned)(lrow * 64 + lcg * 16);
;     const int koff = (int)((blockIdx.x >> 3) + (blockIdx.x & 7) * 4) & (KT - 1);
;     auto issue_one = [&](int kt, int b, int i) {
;         const int row = lrow + 128 * i;
;         if ((NCH % 512 == 0) || (i < NCH / 512) || row < ROWS) {
;             const int kq = (kt + koff) & (KT - 1);
;             const char* ua = (const char*)A + (size_t)((DBG & 1) ? 0 : kq) * (BM * 64);
;             const char* ub = (const char*)Bt + (size_t)((DBG & 2) ? 0 : kq) * ((size_t)ldbk * 2);
;             const char* src;
;             if (BM % 128 == 0) src = (i < BM / 128) ? (ua + i * 8192 + loff) : (ub + (i * 128 - BM) * 64 + loff);
;             else if (i == 0) src = (lrow < BM) ? (ua + loff) : (ub + loff - BM * 64);
;             else src = ub + (i * 128 - BM) * 64 + loff;
;             __builtin_amdgcn_global_load_lds((const unsigned*)src, (unsigned*)(lds + b * BUF + i * 8192 + tid * 16), 16, 0, 0);
;         }
;     };
;     auto issue = [&](int kt, int b) {
; #pragma unroll
;         for (int i = 0; i < NIT; ++i) issue_one(kt, b, i);
;     };
;     auto compute = [&](int cb, bool do_issue, int ikt, int ib) {
;         const char* base = lds + cb * BUF;
;         bf16x8 af[MT], bfr[NT];
; #pragma unroll
;         for (int nt = 0; nt < NT; ++nt) {
;             const int br = BM + (nt / NTS) * (BN / NSEG) + wc * (NTS * 16) + (nt % NTS) * 16;
;             bfr[nt] = *(const bf16x8*)(base + (br + l15) * 64 + rsw);
;         }
; #pragma unroll
;         for (int mt = 0; mt < MT; ++mt) af[mt] = *(const bf16x8*)(base + (wr * WM + mt * 16 + l15) * 64 + rsw);
;     ...
;     __syncthreads();
; #pragma unroll
;     for (int d = 0; d < D; ++d) issue(d, d);
;     int cb = 0, ib = D;
;     for (int kt = 0; kt < KT; ++kt) {
;         if (D > 1 && kt + D - 1 < KT) wait_vm<(D - 1) * NIT>(); else wait_vm<0>();
;         raw_barrier();
;         compute(cb, kt + D < KT, kt + D, ib);
	global_load_lds_dwordx4 v[2:3], off
	v_lshl_add_u64 v[2:3], s[14:15], 0, v[0:1]
	s_mov_b32 m0, s13
	v_readfirstlane_b32 s13, v10
	global_load_lds_dwordx4 v0, s[14:15]
	v_lshl_add_u64 v[4:5], v[2:3], 0, s[76:77]
	s_mov_b32 m0, s13
	v_lshl_add_u64 v[2:3], v[2:3], 0, s[80:81]
	global_load_lds_dwordx4 v[4:5], off
	v_add_u32_e32 v4, 0x6000, v102
	v_readlane_b32 s14, v243, 5
	v_readfirstlane_b32 s13, v4
	v_add_u32_e32 v4, 0x8000, v102
	s_mov_b32 m0, s13
	v_readfirstlane_b32 s13, v4
	global_load_lds_dwordx4 v[2:3], off
	v_readlane_b32 s15, v243, 6
	s_mov_b32 m0, s13
	v_readlane_b32 s13, v243, 7
	v_lshl_add_u64 v[2:3], v[98:99], 0, s[14:15]
	s_add_u32 s14, s8, s13
	v_add_u32_e32 v4, 0xa000, v102
	s_addc_u32 s15, s9, 0
	v_readfirstlane_b32 s13, v4
	v_add_u32_e32 v10, 0xc000, v102
	global_load_lds_dwordx4 v[2:3], off
	v_lshl_add_u64 v[2:3], s[14:15], 0, v[0:1]
	s_mov_b32 m0, s13
	v_readfirstlane_b32 s13, v10
	global_load_lds_dwordx4 v0, s[14:15]
	v_lshl_add_u64 v[4:5], v[2:3], 0, s[76:77]
	s_mov_b32 m0, s13
	v_lshl_add_u64 v[2:3], v[2:3], 0, s[80:81]
	global_load_lds_dwordx4 v[4:5], off
	v_add_u32_e32 v4, 0xe000, v102
	s_mov_b32 s7, 4
	v_readfirstlane_b32 s13, v4
	s_mov_b32 m0, s13
	s_mov_b32 s11, 2
	global_load_lds_dwordx4 v[2:3], off
	v_bitop3_b32 v3, v6, 48, v9 bitop3:0x48
	v_mul_i32_i24_e32 v2, 4, v8
	v_add_u32_e32 v103, 0, v3
	v_lshlrev_b32_e32 v3, 6, v6
	v_sub_u32_e32 v2, v7, v2
	v_and_b32_e32 v3, 0x3c0, v3
	v_lshl_or_b32 v104, v2, 11, v3
	v_mov_b32_e32 v2, 0
	s_mov_b32 s12, 0
	v_lshl_or_b32 v105, v8, 12, v3
	v_lshl_add_u64 v[100:101], s[8:9], 0, v[0:1]
	v_readlane_b32 s13, v243, 24
	v_mov_b32_e32 v3, v2
	v_mov_b32_e32 v4, v2
	v_mov_b32_e32 v5, v2
	v_mov_b32_e32 v6, v2
	v_mov_b32_e32 v7, v2
	v_mov_b32_e32 v8, v2
	v_mov_b32_e32 v9, v2
	v_mov_b32_e32 v10, v2
	v_mov_b32_e32 v11, v2
	v_mov_b32_e32 v12, v2
	v_mov_b32_e32 v13, v2
	v_mov_b32_e32 v14, v2
	v_mov_b32_e32 v15, v2
	v_mov_b32_e32 v16, v2
	v_mov_b32_e32 v17, v2
	v_mov_b32_e32 v18, v2
	v_mov_b32_e32 v19, v2
	v_mov_b32_e32 v20, v2
	v_mov_b32_e32 v21, v2
	v_mov_b32_e32 v22, v2
	v_mov_b32_e32 v23, v2
	v_mov_b32_e32 v24, v2
	v_mov_b32_e32 v25, v2
	v_mov_b32_e32 v26, v2
	v_mov_b32_e32 v27, v2
	v_mov_b32_e32 v28, v2
	v_mov_b32_e32 v29, v2
	v_mov_b32_e32 v30, v2
	v_mov_b32_e32 v31, v2
	v_mov_b32_e32 v32, v2
	v_mov_b32_e32 v33, v2
	v_mov_b32_e32 v34, v2
	v_mov_b32_e32 v35, v2
	v_mov_b32_e32 v36, v2
	v_mov_b32_e32 v37, v2
	v_mov_b32_e32 v38, v2
	v_mov_b32_e32 v39, v2
	v_mov_b32_e32 v40, v2
	v_mov_b32_e32 v41, v2
	v_mov_b32_e32 v42, v2
	v_mov_b32_e32 v43, v2
	v_mov_b32_e32 v44, v2
	v_mov_b32_e32 v45, v2
	v_mov_b32_e32 v46, v2
	v_mov_b32_e32 v47, v2
	v_mov_b32_e32 v48, v2
	v_mov_b32_e32 v49, v2
	v_mov_b32_e32 v50, v2
	v_mov_b32_e32 v51, v2
	v_mov_b32_e32 v52, v2
	v_mov_b32_e32 v53, v2
	v_mov_b32_e32 v54, v2
	v_mov_b32_e32 v55, v2
	v_mov_b32_e32 v56, v2
	v_mov_b32_e32 v57, v2
	v_mov_b32_e32 v58, v2
	v_mov_b32_e32 v59, v2
	v_mov_b32_e32 v60, v2
	v_mov_b32_e32 v61, v2
	v_mov_b32_e32 v62, v2
	v_mov_b32_e32 v63, v2
	v_mov_b32_e32 v64, v2
	v_mov_b32_e32 v65, v2
	v_mov_b32_e32 v66, v2
	v_mov_b32_e32 v67, v2
	v_mov_b32_e32 v68, v2
	v_mov_b32_e32 v69, v2
	v_mov_b32_e32 v70, v2
	v_mov_b32_e32 v71, v2
	v_mov_b32_e32 v72, v2
	v_mov_b32_e32 v73, v2
	v_mov_b32_e32 v74, v2
	v_mov_b32_e32 v75, v2
	v_mov_b32_e32 v76, v2
	v_mov_b32_e32 v77, v2
	v_mov_b32_e32 v78, v2
	v_mov_b32_e32 v79, v2
	v_mov_b32_e32 v80, v2
	v_mov_b32_e32 v81, v2
	v_mov_b32_e32 v82, v2
	v_mov_b32_e32 v83, v2
	v_mov_b32_e32 v84, v2
	v_mov_b32_e32 v85, v2
	v_mov_b32_e32 v86, v2
	v_mov_b32_e32 v87, v2
	v_mov_b32_e32 v88, v2
	v_mov_b32_e32 v89, v2
	v_mov_b32_e32 v90, v2
	v_mov_b32_e32 v91, v2
	v_mov_b32_e32 v92, v2
	v_mov_b32_e32 v93, v2
	v_mov_b32_e32 v94, v2
	v_mov_b32_e32 v95, v2
	v_mov_b32_e32 v96, v2
	v_mov_b32_e32 v97, v2
	v_readfirstlane_b32 s40, v212
	s_nop 3
	s_cmp_lt_u32 s40, 0x100
	s_cbranch_scc0 .Lpa_c_entry
	s_lshl_b32 s13, s40, 5
	s_lshl_b32 s40, s40, 4
	v_add_u32_e32 v227, s40, v0
	v_readfirstlane_b32 s14, v98
	v_readfirstlane_b32 s15, v99
	v_readfirstlane_b32 s40, v0
	s_nop 3
	s_sub_u32 vcc_lo, s14, s40
	s_subb_u32 vcc_hi, s15, 0
	s_mul_i32 s14, s11, 0x8000
	s_add_u32 s14, s14, s13
	s_mov_b32 m0, s14
	s_add_i32 s40, s59, s7
	s_and_b32 s40, s40, 62
	s_lshl_b32 s14, s40, 12
	s_add_u32 s14, vcc_lo, s14
	s_addc_u32 s15, vcc_hi, 0
	s_mul_i32 s40, s40, 0x14000
	global_load_lds_dwordx4 v227, s[14:15]
	global_load_lds_dwordx4 v227, s[14:15] offset:1024
	s_add_u32 s14, s8, s40
	s_addc_u32 s15, s9, 0
	s_add_u32 m0, m0, 0x2000
	s_nop 0
	global_load_lds_dwordx4 v227, s[14:15]
	global_load_lds_dwordx4 v227, s[14:15] offset:1024
	s_add_u32 s14, s14, 0x2000
	s_addc_u32 s15, s15, 0
	s_add_u32 m0, m0, 0x2000
	s_nop 0
	global_load_lds_dwordx4 v227, s[14:15]
	global_load_lds_dwordx4 v227, s[14:15] offset:1024
	s_add_u32 s14, s14, 0x2000
	s_addc_u32 s15, s15, 0
	s_add_u32 m0, m0, 0x2000
	s_nop 0
	global_load_lds_dwordx4 v227, s[14:15]
	global_load_lds_dwordx4 v227, s[14:15] offset:1024
	s_add_i32 s7, s7, 2
	s_mov_b32 s11, 0
	s_mov_b32 s12, 1
	s_waitcnt vmcnt(12)
	s_barrier
	v_add_u32_e32 v225, v103, v104
	v_add_u32_e32 v224, v103, v105
	ds_read_b128 v[106:109], v224
	ds_read_b128 v[118:121], v224 offset:1024
	ds_read_b128 v[138:141], v224 offset:2048
	ds_read_b128 v[110:113], v225 offset:8192
	ds_read_b128 v[114:117], v225 offset:9216
	ds_read_b128 v[122:125], v225 offset:16384
	ds_read_b128 v[126:129], v225 offset:17408
	ds_read_b128 v[130:133], v225 offset:24576
	ds_read_b128 v[134:137], v225 offset:25600
	ds_read_b128 v[142:145], v224 offset:3072
	.p2align 6

; template <int N> DI void wait_vm() { asm volatile("s_waitcnt vmcnt(%0)" ::"n"(N) : "memory"); }
; DI void raw_barrier() { asm volatile("" ::: "memory"); __builtin_amdgcn_s_barrier(); asm volatile("" ::: "memory"); }
;     ...
;     auto compute = [&](int cb, bool do_issue, int ikt, int ib) {
;         const char* base = lds + cb * BUF;
;         bf16x8 af[MT], bfr[NT];
; #pragma unroll
;         for (int nt = 0; nt < NT; ++nt) {
;             const int br = BM + (nt / NTS) * (BN / NSEG) + wc * (NTS * 16) + (nt % NTS) * 16;
;             bfr[nt] = *(const bf16x8*)(base + (br + l15) * 64 + rsw);
;         }
; #pragma unroll
;         for (int mt = 0; mt < MT; ++mt) af[mt] = *(const bf16x8*)(base + (wr * WM + mt * 16 + l15) * 64 + rsw);
;     ...
;     for (int kt = 0; kt < KT; ++kt) {
;         if (D > 1 && kt + D - 1 < KT) wait_vm<(D - 1) * NIT>(); else wait_vm<0>();
;         raw_barrier();
.Lpa_c_entry:
	s_add_i32 s7, s7, 2
	s_mov_b32 s12, 1
	s_waitcnt vmcnt(4)
	s_barrier
	v_add_u32_e32 v225, v103, v104
	v_add_u32_e32 v224, v103, v105
	ds_read_b128 v[106:109], v224
	ds_read_b128 v[118:121], v224 offset:1024
	ds_read_b128 v[138:141], v224 offset:2048
	ds_read_b128 v[110:113], v225 offset:8192
	ds_read_b128 v[114:117], v225 offset:9216
	ds_read_b128 v[122:125], v225 offset:16384
	ds_read_b128 v[126:129], v225 offset:17408
	ds_read_b128 v[130:133], v225 offset:24576
	ds_read_b128 v[134:137], v225 offset:25600
	ds_read_b128 v[142:145], v224 offset:3072
	.p2align 6

;     constexpr int WM = BM / WR, WN = BN / WC, MT = WM / 16, NT = WN / 16, ROWS = BM + BN, NCH = ROWS * 4, NIT = (NCH + 511) / 512, BUF = ROWS * 64, KT = 32;
;     constexpr int NTS = NT / NSEG, D = NST - 1;
;     static_assert(D == 1 || (NCH % 512 == 0), "deep ring needs a uniform per-thread load count");
;     const int tid = opaque_tid(), lane = tid & 63, wid = tid >> 6, wr = wid / WC, wc = wid % WC, l15 = lane & 15, quad = lane >> 4;
;     const int lrow = tid >> 2, lc = tid & 3;
;     const int lcg = lc ^ ((0 - (tid >> 4)) & 3);
;     const int rsw = (quad ^ ((0 - (l15 >> 2)) & 3)) << 4;
; #pragma unroll
;     for (int mt = 0; mt < MT; ++mt)
; #pragma unroll
;         for (int nt = 0; nt < NT; ++nt) acc[mt][nt] = (f32x4){0.f, 0.f, 0.f, 0.f};
;     const unsigned loff = (unsigned)(lrow * 64 + lcg * 16);
;     const int koff = (int)((blockIdx.x >> 3) + (blockIdx.x & 7) * 4) & (KT - 1);
;     auto issue_one = [&](int kt, int b, int i) {
;         const int row = lrow + 128 * i;
;         if ((NCH % 512 == 0) || (i < NCH / 512) || row < ROWS) {
;             const int kq = (kt + koff) & (KT - 1);
;             const char* ua = (const char*)A + (size_t)((DBG & 1) ? 0 : kq) * (BM * 64);
;             const char* ub = (const char*)Bt + (size_t)((DBG & 2) ? 0 : kq) * ((size_t)ldbk * 2);
;             const char* src;
;             if (BM % 128 == 0) src = (i < BM / 128) ? (ua + i * 8192 + loff) : (ub + (i * 128 - BM) * 64 + loff);
;             else if (i == 0) src = (lrow < BM) ? (ua + loff) : (ub + loff - BM * 64);
;             else src = ub + (i * 128 - BM) * 64 + loff;
;             __builtin_amdgcn_global_load_lds((const unsigned*)src, (unsigned*)(lds + b * BUF + i * 8192 + tid * 16), 16, 0, 0);
;         }
;     };
;     auto issue = [&](int kt, int b) {
; #pragma unroll
;         for (int i = 0; i < NIT; ++i) issue_one(kt, b, i);
;     ...
;     __syncthreads();
; #pragma unroll
;     for (int d = 0; d < D; ++d) issue(d, d);
;     int cb = 0, ib = D;
;     for (int kt = 0; kt < KT; ++kt) {
;         if (D > 1 && kt + D - 1 < KT) wait_vm<(D - 1) * NIT>(); else wait_vm<0>();
; DI void unit_KV(const Params& p, char* lds, int l, int mtile, int q) {
;     ...
;     gemm_main<128, 128, 2, 4, 1, true, 3>(WS_PTR(const bf16_t, OFF_MEMB) + (size_t)mtile * 128 * 1024, WS_PTR(const bf16_t, OFF_WKV) + (size_t)l * 524288 + (size_t)(128 * q) * 32, 512 * 32, lds, acc);
.LBB0_859:
	s_andn2_b64 vcc, exec, s[6:7]
	s_cbranch_vccnz .LBB0_891
	s_bfe_u32 s0, s2, 0x50002
	s_lshr_b32 s1, s3, 7
	s_and_b32 s3, s2, 3
	s_lshl_b32 s6, s0, 18
	v_readlane_b32 s7, v244, 38
	v_mov_b32_e32 v44, v212
	s_add_u32 s8, s7, s6
	v_readlane_b32 s6, v244, 39
	v_mov_b32_e32 v4, v212
	s_addc_u32 s9, s6, 0
	s_lshl_b32 s6, s1, 20
	v_readlane_b32 s7, v243, 18
	s_add_u32 s7, s7, s6
	v_lshrrev_b32_e32 v0, 4, v4
	v_readlane_b32 s10, v243, 19
	v_sub_u32_e32 v0, 0, v0
	s_addc_u32 s11, s10, 0
	s_lshl_b32 s10, s3, 13
	v_xor_b32_e32 v0, v4, v0
	v_lshlrev_b32_e32 v5, 4, v4
	s_add_u32 s10, s7, s10
	v_and_b32_e32 v2, 0xffffffc0, v5
	v_lshlrev_b32_e32 v0, 4, v0
	s_addc_u32 s11, s11, 0
	v_and_or_b32 v0, v0, 48, v2
	v_lshl_add_u64 v[34:35], s[8:9], 0, v[0:1]
	v_lshl_add_u64 v[36:37], s[10:11], 0, v[0:1]
	v_readlane_b32 s8, v243, 25
	v_add_u32_e32 v0, 0, v5
	v_readlane_b32 s9, v243, 26
	v_readfirstlane_b32 s7, v0
	v_add_u32_e32 v5, 0x2000, v0
	v_lshl_add_u64 v[2:3], v[34:35], 0, s[8:9]
	s_mov_b32 m0, s7
	v_readfirstlane_b32 s7, v5
	v_readlane_b32 s8, v243, 5
	s_waitcnt lgkmcnt(0)
	s_barrier
	global_load_lds_dwordx4 v[2:3], off
	v_lshl_add_u64 v[2:3], v[36:37], 0, s[74:75]
	s_mov_b32 m0, s7
	v_readlane_b32 s9, v243, 6
	v_add_u32_e32 v5, 0x4000, v0
	global_load_lds_dwordx4 v[2:3], off
	v_lshl_add_u64 v[2:3], v[34:35], 0, s[8:9]
	v_readfirstlane_b32 s7, v5
	v_readlane_b32 s8, v243, 20
	v_add_u32_e32 v5, 0x6000, v0
	s_mov_b32 m0, s7
	v_readlane_b32 s9, v243, 21
	v_readfirstlane_b32 s7, v5
	global_load_lds_dwordx4 v[2:3], off
	v_lshl_add_u64 v[2:3], v[36:37], 0, s[8:9]
	s_mov_b32 m0, s7
	v_lshlrev_b32_e32 v5, 2, v4
	global_load_lds_dwordx4 v[2:3], off
	v_ashrrev_i32_e32 v2, 6, v4
	v_lshrrev_b32_e32 v3, 30, v2
	v_add_u32_e32 v3, v2, v3
	v_and_b32_e32 v5, 48, v5
	v_ashrrev_i32_e32 v3, 2, v3
	v_sub_u32_e32 v5, 0, v5
	v_mul_i32_i24_e32 v6, 4, v3
	v_bitop3_b32 v5, v4, 48, v5 bitop3:0x48
	v_lshlrev_b32_e32 v4, 6, v4
	v_sub_u32_e32 v2, v2, v6
	v_and_b32_e32 v4, 0x3c0, v4
	v_lshl_or_b32 v40, v2, 11, v4
	v_mov_b32_e32 v2, 0
	s_mov_b32 s9, 2
	s_mov_b32 s7, 0
	v_add_u32_e32 v38, 0, v5
	v_lshl_or_b32 v39, v3, 12, v4
	v_readlane_b32 s8, v243, 27
	s_mov_b32 s10, 0
	v_mov_b32_e32 v3, v2
	v_mov_b32_e32 v4, v2
	v_mov_b32_e32 v5, v2
	v_mov_b32_e32 v6, v2
	v_mov_b32_e32 v7, v2
	v_mov_b32_e32 v8, v2
	v_mov_b32_e32 v9, v2
	v_mov_b32_e32 v10, v2
	v_mov_b32_e32 v11, v2
	v_mov_b32_e32 v12, v2
	v_mov_b32_e32 v13, v2
	v_mov_b32_e32 v14, v2
	v_mov_b32_e32 v15, v2
	v_mov_b32_e32 v16, v2
	v_mov_b32_e32 v17, v2
	v_mov_b32_e32 v18, v2
	v_mov_b32_e32 v19, v2
	v_mov_b32_e32 v20, v2
	v_mov_b32_e32 v21, v2
	v_mov_b32_e32 v22, v2
	v_mov_b32_e32 v23, v2
	v_mov_b32_e32 v24, v2
	v_mov_b32_e32 v25, v2
	v_mov_b32_e32 v26, v2
	v_mov_b32_e32 v27, v2
	v_mov_b32_e32 v28, v2
	v_mov_b32_e32 v29, v2
	v_mov_b32_e32 v30, v2
	v_mov_b32_e32 v31, v2
	v_mov_b32_e32 v32, v2
	v_mov_b32_e32 v33, v2
	v_readfirstlane_b32 s90, v212
	s_nop 3
	s_cmp_lt_u32 s90, 0x100
	s_cbranch_scc0 .Lpkv_c_entry
	v_readfirstlane_b32 s94, v34
	v_readfirstlane_b32 s95, v35
	v_readfirstlane_b32 s92, v36
	v_readfirstlane_b32 s93, v37
	s_nop 3
	s_lshl_b32 s8, s90, 5
	s_lshl_b32 s40, s90, 4
	v_subrev_u32_e32 v227, s94, v34
	v_add_u32_e32 v227, s8, v227
	s_sub_u32 vcc_lo, s94, s40
	s_subb_u32 vcc_hi, s95, 0
	s_sub_u32 s92, s92, s40
	s_subb_u32 s93, s93, 0
	s_mov_b32 s7, 4
	s_mov_b32 s9, 2
	s_lshl_b32 s94, s9, 14
	s_add_u32 s94, s94, s8
	s_mov_b32 m0, s94
	s_add_i32 s40, s59, s7
	s_and_b32 s40, s40, 62
	s_lshl_b32 s94, s40, 12
	s_add_u32 s94, vcc_lo, s94
	s_addc_u32 s95, vcc_hi, 0
	s_lshl_b32 s40, s40, 14
	global_load_lds_dwordx4 v227, s[94:95]
	global_load_lds_dwordx4 v227, s[94:95] offset:1024
	s_add_u32 s94, s92, s40
	s_addc_u32 s95, s93, 0
	s_add_u32 m0, m0, 0x2000
	s_nop 0
	global_load_lds_dwordx4 v227, s[94:95]
	global_load_lds_dwordx4 v227, s[94:95] offset:1024
	s_mov_b32 s7, 6
	s_mov_b32 s9, 3
	s_lshl_b32 s94, s9, 14
	s_add_u32 s94, s94, s8
	s_mov_b32 m0, s94
	s_add_i32 s40, s59, s7
	s_and_b32 s40, s40, 62
	s_lshl_b32 s94, s40, 12
	s_add_u32 s94, vcc_lo, s94
	s_addc_u32 s95, vcc_hi, 0
	s_lshl_b32 s40, s40, 14
	global_load_lds_dwordx4 v227, s[94:95]
	global_load_lds_dwordx4 v227, s[94:95] offset:1024
	s_add_u32 s94, s92, s40
	s_addc_u32 s95, s93, 0
	s_add_u32 m0, m0, 0x2000
	s_nop 0
	global_load_lds_dwordx4 v227, s[94:95]
	global_load_lds_dwordx4 v227, s[94:95] offset:1024
	s_mov_b32 s7, 8
	s_mov_b32 s9, 4
	s_lshl_b32 s94, s9, 14
	s_add_u32 s94, s94, s8
	s_mov_b32 m0, s94
	s_add_i32 s40, s59, s7
	s_and_b32 s40, s40, 62
	s_lshl_b32 s94, s40, 12
	s_add_u32 s94, vcc_lo, s94
	s_addc_u32 s95, vcc_hi, 0
	s_lshl_b32 s40, s40, 14
	global_load_lds_dwordx4 v227, s[94:95]
	global_load_lds_dwordx4 v227, s[94:95] offset:1024
	s_add_u32 s94, s92, s40
	s_addc_u32 s95, s93, 0
	s_add_u32 m0, m0, 0x2000
	s_nop 0
	global_load_lds_dwordx4 v227, s[94:95]
	global_load_lds_dwordx4 v227, s[94:95] offset:1024
	s_mov_b32 s7, 10
	s_mov_b32 s9, 5
	s_lshl_b32 s94, s9, 14
	s_add_u32 s94, s94, s8
	s_mov_b32 m0, s94
	s_add_i32 s40, s59, s7
	s_and_b32 s40, s40, 62
	s_lshl_b32 s94, s40, 12
	s_add_u32 s94, vcc_lo, s94
	s_addc_u32 s95, vcc_hi, 0
	s_lshl_b32 s40, s40, 14
	global_load_lds_dwordx4 v227, s[94:95]
	global_load_lds_dwordx4 v227, s[94:95] offset:1024
	s_add_u32 s94, s92, s40
	s_addc_u32 s95, s93, 0
	s_add_u32 m0, m0, 0x2000
	s_nop 0
	global_load_lds_dwordx4 v227, s[94:95]
	global_load_lds_dwordx4 v227, s[94:95] offset:1024
	s_mov_b32 s7, 12
	s_mov_b32 s9, 6
	s_lshl_b32 s94, s9, 14
	s_add_u32 s94, s94, s8
	s_mov_b32 m0, s94
	s_add_i32 s40, s59, s7
	s_and_b32 s40, s40, 62
	s_lshl_b32 s94, s40, 12
	s_add_u32 s94, vcc_lo, s94
	s_addc_u32 s95, vcc_hi, 0
	s_lshl_b32 s40, s40, 14
	global_load_lds_dwordx4 v227, s[94:95]
	global_load_lds_dwordx4 v227, s[94:95] offset:1024
	s_add_u32 s94, s92, s40
	s_addc_u32 s95, s93, 0
	s_add_u32 m0, m0, 0x2000
	s_nop 0
	global_load_lds_dwordx4 v227, s[94:95]
	global_load_lds_dwordx4 v227, s[94:95] offset:1024
	s_mov_b32 s7, 14
	s_mov_b32 s9, 7
	s_lshl_b32 s94, s9, 14
	s_add_u32 s94, s94, s8
	s_mov_b32 m0, s94
	s_add_i32 s40, s59, s7
	s_and_b32 s40, s40, 62
	s_lshl_b32 s94, s40, 12
	s_add_u32 s94, vcc_lo, s94
	s_addc_u32 s95, vcc_hi, 0
	s_lshl_b32 s40, s40, 14
	global_load_lds_dwordx4 v227, s[94:95]
	global_load_lds_dwordx4 v227, s[94:95] offset:1024
	s_add_u32 s94, s92, s40
	s_addc_u32 s95, s93, 0
	s_add_u32 m0, m0, 0x2000
	s_nop 0
	global_load_lds_dwordx4 v227, s[94:95]
	global_load_lds_dwordx4 v227, s[94:95] offset:1024
	s_mov_b32 s7, 16
	s_mov_b32 s9, 0
	s_mov_b32 s10, 1
	s_waitcnt vmcnt(26)
	s_barrier
	v_add_u32_e32 v225, v38, v40
	v_add_u32_e32 v224, v38, v39
	ds_read_b128 v[54:57], v224
	ds_read_b128 v[58:61], v224 offset:1024
	ds_read_b128 v[62:65], v224 offset:2048
	ds_read_b128 v[46:49], v225 offset:8192
	ds_read_b128 v[50:53], v225 offset:9216
	ds_read_b128 v[216:219], v224 offset:3072
	.p2align 6

; template <int N> DI void wait_vm() { asm volatile("s_waitcnt vmcnt(%0)" ::"n"(N) : "memory"); }
; DI void raw_barrier() { asm volatile("" ::: "memory"); __builtin_amdgcn_s_barrier(); asm volatile("" ::: "memory"); }
;     ...
;     auto compute = [&](int cb, bool do_issue, int ikt, int ib) {
;         const char* base = lds + cb * BUF;
;         bf16x8 af[MT], bfr[NT];
; #pragma unroll
;         for (int nt = 0; nt < NT; ++nt) {
;             const int br = BM + (nt / NTS) * (BN / NSEG) + wc * (NTS * 16) + (nt % NTS) * 16;
;             bfr[nt] = *(const bf16x8*)(base + (br + l15) * 64 + rsw);
;         }
; #pragma unroll
;         for (int mt = 0; mt < MT; ++mt) af[mt] = *(const bf16x8*)(base + (wr * WM + mt * 16 + l15) * 64 + rsw);
;     ...
;     for (int kt = 0; kt < KT; ++kt) {
;         if (D > 1 && kt + D - 1 < KT) wait_vm<(D - 1) * NIT>(); else wait_vm<0>();
;         raw_barrier();
.Lpkv_c_entry:
	s_mov_b32 s7, 16
	s_mov_b32 s10, 1
	s_waitcnt vmcnt(2)
	s_barrier
	v_add_u32_e32 v225, v38, v40
	v_add_u32_e32 v224, v38, v39
	ds_read_b128 v[54:57], v224
	ds_read_b128 v[58:61], v224 offset:1024
	ds_read_b128 v[62:65], v224 offset:2048
	ds_read_b128 v[46:49], v225 offset:8192
	ds_read_b128 v[50:53], v225 offset:9216
	ds_read_b128 v[216:219], v224 offset:3072
	.p2align 6

; DI int opaque_tid() { int t = threadIdx.x; asm volatile("" : "+v"(t)); return t; }
;     constexpr int WM = BM / WR, WN = BN / WC, MT = WM / 16, NT = WN / 16, ROWS = BM + BN, NCH = ROWS * 4, NIT = (NCH + 511) / 512, BUF = ROWS * 64, KT = 32;
;     constexpr int NTS = NT / NSEG, D = NST - 1;
;     static_assert(D == 1 || (NCH % 512 == 0), "deep ring needs a uniform per-thread load count");
;     const int tid = opaque_tid(), lane = tid & 63, wid = tid >> 6, wr = wid / WC, wc = wid % WC, l15 = lane & 15, quad = lane >> 4;
;     const int lrow = tid >> 2, lc = tid & 3;
;     const int lcg = lc ^ ((0 - (tid >> 4)) & 3);
;     const int rsw = (quad ^ ((0 - (l15 >> 2)) & 3)) << 4;
; #pragma unroll
;     for (int mt = 0; mt < MT; ++mt)
; #pragma unroll
;         for (int nt = 0; nt < NT; ++nt) acc[mt][nt] = (f32x4){0.f, 0.f, 0.f, 0.f};
;     const unsigned loff = (unsigned)(lrow * 64 + lcg * 16);
;     const int koff = (int)((blockIdx.x >> 3) + (blockIdx.x & 7) * 4) & (KT - 1);
;     auto issue_one = [&](int kt, int b, int i) {
;         const int row = lrow + 128 * i;
;         if ((NCH % 512 == 0) || (i < NCH / 512) || row < ROWS) {
;             const int kq = (kt + koff) & (KT - 1);
;             const char* ua = (const char*)A + (size_t)((DBG & 1) ? 0 : kq) * (BM * 64);
;             const char* ub = (const char*)Bt + (size_t)((DBG & 2) ? 0 : kq) * ((size_t)ldbk * 2);
;             const char* src;
;             if (BM % 128 == 0) src = (i < BM / 128) ? (ua + i * 8192 + loff) : (ub + (i * 128 - BM) * 64 + loff);
;             else if (i == 0) src = (lrow < BM) ? (ua + loff) : (ub + loff - BM * 64);
;             else src = ub + (i * 128 - BM) * 64 + loff;
;             __builtin_amdgcn_global_load_lds((const unsigned*)src, (unsigned*)(lds + b * BUF + i * 8192 + tid * 16), 16, 0, 0);
;         }
;     };
;     auto issue = [&](int kt, int b) {
; #pragma unroll
;         for (int i = 0; i < NIT; ++i) issue_one(kt, b, i);
;     ...
;     __syncthreads();
; #pragma unroll
;     for (int d = 0; d < D; ++d) issue(d, d);
; DI void unit_B1(const Params& p, char* lds, int l, int chunk) {
;     ...
;     gemm_main<128, 512, 2, 4, 1, true, 3>(xb + (size_t)chunk * 128 * 1024, WS_PTR(const bf16_t, OFF_WIN) + (size_t)l * 2560 * 1024 + (size_t)1536 * 32, 2560 * 32, lds, acc);
.LBB0_892:
	s_andn2_b64 vcc, exec, s[6:7]
	s_cbranch_vccnz .LBB0_662
	v_mov_b32_e32 v135, v212
	v_mov_b32_e32 v4, v212
	s_ashr_i32 s3, s2, 31
	v_ashrrev_i32_e32 v5, 6, v4
	v_lshrrev_b32_e32 v0, 30, v5
	v_add_u32_e32 v0, v5, v0
	v_ashrrev_i32_e32 v6, 2, v0
	v_lshrrev_b32_e32 v0, 4, v4
	v_sub_u32_e32 v0, 0, v0
	v_lshlrev_b32_e32 v2, 2, v4
	s_lshl_b64 s[0:1], s[2:3], 18
	v_readlane_b32 s6, v243, 56
	v_and_b32_e32 v2, 48, v2
	v_xor_b32_e32 v0, v4, v0
	v_lshlrev_b32_e32 v8, 4, v4
	s_add_u32 s8, s6, s0
	v_readlane_b32 s0, v243, 40
	v_sub_u32_e32 v7, 0, v2
	v_and_b32_e32 v2, 0xffffffc0, v8
	v_lshlrev_b32_e32 v0, 4, v0
	s_addc_u32 s9, s0, s1
	v_and_or_b32 v0, v0, 48, v2
	v_lshl_add_u64 v[130:131], s[8:9], 0, v[0:1]
	v_readlane_b32 s8, v243, 25
	v_add_u32_e32 v134, 0, v8
	v_readlane_b32 s9, v243, 26
	v_readfirstlane_b32 s7, v134
	s_mov_b32 m0, s7
	v_lshl_add_u64 v[2:3], v[130:131], 0, s[8:9]
	s_waitcnt lgkmcnt(0)
	s_barrier
	global_load_lds_dwordx4 v[2:3], off
	v_add_u32_e32 v2, 0x2000, v134
	v_readlane_b32 s8, v243, 42
	v_readfirstlane_b32 s7, v2
	s_mov_b32 m0, s7
	v_readlane_b32 s9, v243, 43
	v_add_u32_e32 v2, 0x4000, v134
	v_add_u32_e32 v9, 0xa000, v134
	v_readfirstlane_b32 s7, v2
	v_add_u32_e32 v2, 0x6000, v134
	s_mov_b32 s1, 2
	global_load_lds_dwordx4 v0, s[8:9]
	v_readlane_b32 s8, v243, 44
	s_mov_b32 m0, s7
	v_readlane_b32 s9, v243, 45
	v_readfirstlane_b32 s7, v2
	v_add_u32_e32 v2, 0x8000, v134
	s_mov_b32 s0, 4
	s_mov_b32 s6, 0
	v_lshl_add_u64 v[132:133], s[48:49], 0, v[0:1]
	global_load_lds_dwordx4 v0, s[8:9]
	v_readlane_b32 s8, v243, 46
	s_mov_b32 m0, s7
	v_readlane_b32 s9, v243, 47
	v_readfirstlane_b32 s7, v2
	s_nop 3
	global_load_lds_dwordx4 v0, s[8:9]
	v_readlane_b32 s8, v243, 48
	s_mov_b32 m0, s7
	v_readlane_b32 s9, v243, 49
	v_readfirstlane_b32 s7, v9
	s_nop 3
	global_load_lds_dwordx4 v0, s[8:9]
	v_readlane_b32 s8, v243, 5
	v_readlane_b32 s9, v243, 6
	s_mov_b32 m0, s7
	s_nop 0
	v_lshl_add_u64 v[2:3], v[130:131], 0, s[8:9]
	global_load_lds_dwordx4 v[2:3], off
	v_add_u32_e32 v2, 0xc000, v134
	v_readlane_b32 s8, v243, 50
	v_readfirstlane_b32 s7, v2
	v_add_u32_e32 v2, 0xe000, v134
	s_mov_b32 m0, s7
	v_readlane_b32 s9, v243, 51
	v_readfirstlane_b32 s7, v2
	v_bitop3_b32 v3, v4, 48, v7 bitop3:0x48
	v_add_u32_e32 v136, 0, v3
	v_lshlrev_b32_e32 v3, 6, v4
	v_and_b32_e32 v3, 0x3c0, v3
	global_load_lds_dwordx4 v0, s[8:9]
	s_mov_b32 m0, s7
	s_add_i32 s7, 0, 0x10000
	v_readlane_b32 s8, v243, 52
	v_add_u32_e32 v2, s7, v8
	v_readlane_b32 s9, v243, 53
	v_readfirstlane_b32 s7, v2
	v_lshl_or_b32 v137, v6, 12, v3
	s_nop 2
	global_load_lds_dwordx4 v0, s[8:9]
	s_mov_b32 m0, s7
	v_readlane_b32 s8, v243, 58
	v_readlane_b32 s7, v243, 31
	v_readlane_b32 s9, v243, 59
	s_nop 0
	v_add_u32_e32 v2, s7, v8
	s_nop 0
	v_readfirstlane_b32 s7, v2
	v_mul_i32_i24_e32 v2, 4, v6
	global_load_lds_dwordx4 v0, s[8:9]
	v_readlane_b32 s8, v243, 54
	s_mov_b32 m0, s7
	v_readlane_b32 s9, v243, 55
	v_sub_u32_e32 v2, v5, v2
	v_lshl_or_b32 v138, v2, 13, v3
	v_mov_b32_e32 v2, 0
	v_readlane_b32 s7, v243, 24
	v_mov_b32_e32 v3, v2
	global_load_lds_dwordx4 v0, s[8:9]
	v_mov_b32_e32 v4, v2
	v_mov_b32_e32 v5, v2
	v_mov_b32_e32 v6, v2
	v_mov_b32_e32 v7, v2
	v_mov_b32_e32 v8, v2
	v_mov_b32_e32 v9, v2
	v_mov_b32_e32 v10, v2
	v_mov_b32_e32 v11, v2
	v_mov_b32_e32 v12, v2
	v_mov_b32_e32 v13, v2
	v_mov_b32_e32 v14, v2
	v_mov_b32_e32 v15, v2
	v_mov_b32_e32 v16, v2
	v_mov_b32_e32 v17, v2
	v_mov_b32_e32 v18, v2
	v_mov_b32_e32 v19, v2
	v_mov_b32_e32 v20, v2
	v_mov_b32_e32 v21, v2
	v_mov_b32_e32 v22, v2
	v_mov_b32_e32 v23, v2
	v_mov_b32_e32 v24, v2
	v_mov_b32_e32 v25, v2
	v_mov_b32_e32 v26, v2
	v_mov_b32_e32 v27, v2
	v_mov_b32_e32 v28, v2
	v_mov_b32_e32 v29, v2
	v_mov_b32_e32 v30, v2
	v_mov_b32_e32 v31, v2
	v_mov_b32_e32 v32, v2
	v_mov_b32_e32 v33, v2
	v_mov_b32_e32 v34, v2
	v_mov_b32_e32 v35, v2
	v_mov_b32_e32 v36, v2
	v_mov_b32_e32 v37, v2
	v_mov_b32_e32 v38, v2
	v_mov_b32_e32 v39, v2
	v_mov_b32_e32 v40, v2
	v_mov_b32_e32 v41, v2
	v_mov_b32_e32 v42, v2
	v_mov_b32_e32 v43, v2
	v_mov_b32_e32 v44, v2
	v_mov_b32_e32 v45, v2
	v_mov_b32_e32 v46, v2
	v_mov_b32_e32 v47, v2
	v_mov_b32_e32 v48, v2
	v_mov_b32_e32 v49, v2
	v_mov_b32_e32 v50, v2
	v_mov_b32_e32 v51, v2
	v_mov_b32_e32 v52, v2
	v_mov_b32_e32 v53, v2
	v_mov_b32_e32 v54, v2
	v_mov_b32_e32 v55, v2
	v_mov_b32_e32 v56, v2
	v_mov_b32_e32 v57, v2
	v_mov_b32_e32 v58, v2
	v_mov_b32_e32 v59, v2
	v_mov_b32_e32 v60, v2
	v_mov_b32_e32 v61, v2
	v_mov_b32_e32 v62, v2
	v_mov_b32_e32 v63, v2
	v_mov_b32_e32 v64, v2
	v_mov_b32_e32 v65, v2
	v_mov_b32_e32 v66, v2
	v_mov_b32_e32 v67, v2
	v_mov_b32_e32 v68, v2
	v_mov_b32_e32 v69, v2
	v_mov_b32_e32 v70, v2
	v_mov_b32_e32 v71, v2
	v_mov_b32_e32 v72, v2
	v_mov_b32_e32 v73, v2
	v_mov_b32_e32 v74, v2
	v_mov_b32_e32 v75, v2
	v_mov_b32_e32 v76, v2
	v_mov_b32_e32 v77, v2
	v_mov_b32_e32 v78, v2
	v_mov_b32_e32 v79, v2
	v_mov_b32_e32 v80, v2
	v_mov_b32_e32 v81, v2
	v_mov_b32_e32 v82, v2
	v_mov_b32_e32 v83, v2
	v_mov_b32_e32 v84, v2
	v_mov_b32_e32 v85, v2
	v_mov_b32_e32 v86, v2
	v_mov_b32_e32 v87, v2
	v_mov_b32_e32 v88, v2
	v_mov_b32_e32 v89, v2
	v_mov_b32_e32 v90, v2
	v_mov_b32_e32 v91, v2
	v_mov_b32_e32 v92, v2
	v_mov_b32_e32 v93, v2
	v_mov_b32_e32 v94, v2
	v_mov_b32_e32 v95, v2
	v_mov_b32_e32 v96, v2
	v_mov_b32_e32 v97, v2
	v_mov_b32_e32 v98, v2
	v_mov_b32_e32 v99, v2
	v_mov_b32_e32 v100, v2
	v_mov_b32_e32 v101, v2
	v_mov_b32_e32 v102, v2
	v_mov_b32_e32 v103, v2
	v_mov_b32_e32 v104, v2
	v_mov_b32_e32 v105, v2
	v_mov_b32_e32 v106, v2
	v_mov_b32_e32 v107, v2
	v_mov_b32_e32 v108, v2
	v_mov_b32_e32 v109, v2
	v_mov_b32_e32 v110, v2
	v_mov_b32_e32 v111, v2
	v_mov_b32_e32 v112, v2
	v_mov_b32_e32 v113, v2
	v_mov_b32_e32 v114, v2
	v_mov_b32_e32 v115, v2
	v_mov_b32_e32 v116, v2
	v_mov_b32_e32 v117, v2
	v_mov_b32_e32 v118, v2
	v_mov_b32_e32 v119, v2
	v_mov_b32_e32 v120, v2
	v_mov_b32_e32 v121, v2
	v_mov_b32_e32 v122, v2
	v_mov_b32_e32 v123, v2
	v_mov_b32_e32 v124, v2
	v_mov_b32_e32 v125, v2
	v_mov_b32_e32 v126, v2
	v_mov_b32_e32 v127, v2
	v_mov_b32_e32 v128, v2
	v_mov_b32_e32 v129, v2
	v_readfirstlane_b32 s40, v212
	s_nop 3
	s_cmp_lt_u32 s40, 0x100
	s_cbranch_scc0 .Lpb1_c_entry
; template <int N> DI void wait_vm() { asm volatile("s_waitcnt vmcnt(%0)" ::"n"(N) : "memory"); }
; DI void raw_barrier() { asm volatile("" ::: "memory"); __builtin_amdgcn_s_barrier(); asm volatile("" ::: "memory"); }
;     ...
;     auto issue_one = [&](int kt, int b, int i) {
;         const int row = lrow + 128 * i;
;         if ((NCH % 512 == 0) || (i < NCH / 512) || row < ROWS) {
;             const int kq = (kt + koff) & (KT - 1);
;             const char* ua = (const char*)A + (size_t)((DBG & 1) ? 0 : kq) * (BM * 64);
;             const char* ub = (const char*)Bt + (size_t)((DBG & 2) ? 0 : kq) * ((size_t)ldbk * 2);
;             const char* src;
;             if (BM % 128 == 0) src = (i < BM / 128) ? (ua + i * 8192 + loff) : (ub + (i * 128 - BM) * 64 + loff);
;             else if (i == 0) src = (lrow < BM) ? (ua + loff) : (ub + loff - BM * 64);
;             else src = ub + (i * 128 - BM) * 64 + loff;
;             __builtin_amdgcn_global_load_lds((const unsigned*)src, (unsigned*)(lds + b * BUF + i * 8192 + tid * 16), 16, 0, 0);
;         }
;     };
;     auto issue = [&](int kt, int b) {
; #pragma unroll
;         for (int i = 0; i < NIT; ++i) issue_one(kt, b, i);
;     };
;     auto compute = [&](int cb, bool do_issue, int ikt, int ib) {
;         const char* base = lds + cb * BUF;
;         bf16x8 af[MT], bfr[NT];
; #pragma unroll
;         for (int nt = 0; nt < NT; ++nt) {
;             const int br = BM + (nt / NTS) * (BN / NSEG) + wc * (NTS * 16) + (nt % NTS) * 16;
;             bfr[nt] = *(const bf16x8*)(base + (br + l15) * 64 + rsw);
;         }
; #pragma unroll
;         for (int mt = 0; mt < MT; ++mt) af[mt] = *(const bf16x8*)(base + (wr * WM + mt * 16 + l15) * 64 + rsw);
;     ...
;     for (int d = 0; d < D; ++d) issue(d, d);
;     int cb = 0, ib = D;
;     for (int kt = 0; kt < KT; ++kt) {
;         if (D > 1 && kt + D - 1 < KT) wait_vm<(D - 1) * NIT>(); else wait_vm<0>();
;         raw_barrier();
	s_lshl_b32 s7, s40, 5
	s_lshl_b32 s40, s40, 4
	v_add_u32_e32 v227, s40, v0
	v_readfirstlane_b32 s8, v130
	v_readfirstlane_b32 s9, v131
	v_readfirstlane_b32 s40, v0
	s_nop 3
	s_sub_u32 vcc_lo, s8, s40
	s_subb_u32 vcc_hi, s9, 0
	s_mul_i32 s8, s1, 0xa000
	s_add_u32 s8, s8, s7
	s_mov_b32 m0, s8
	s_add_i32 s40, s59, s0
	s_and_b32 s40, s40, 62
	s_lshl_b32 s8, s40, 12
	s_add_u32 s8, vcc_lo, s8
	s_addc_u32 s9, vcc_hi, 0
	s_mul_i32 s40, s40, 0x14000
	global_load_lds_dwordx4 v227, s[8:9]
	global_load_lds_dwordx4 v227, s[8:9] offset:1024
	s_add_u32 s8, s48, s40
	s_addc_u32 s9, s49, 0
	s_add_u32 m0, m0, 0x2000
	s_nop 0
	global_load_lds_dwordx4 v227, s[8:9]
	global_load_lds_dwordx4 v227, s[8:9] offset:1024
	s_add_u32 s8, s8, 0x2000
	s_addc_u32 s9, s9, 0
	s_add_u32 m0, m0, 0x2000
	s_nop 0
	global_load_lds_dwordx4 v227, s[8:9]
	global_load_lds_dwordx4 v227, s[8:9] offset:1024
	s_add_u32 s8, s8, 0x2000
	s_addc_u32 s9, s9, 0
	s_add_u32 m0, m0, 0x2000
	s_nop 0
	global_load_lds_dwordx4 v227, s[8:9]
	global_load_lds_dwordx4 v227, s[8:9] offset:1024
	s_add_u32 s8, s8, 0x2000
	s_addc_u32 s9, s9, 0
	s_add_u32 m0, m0, 0x2000
	s_nop 0
	global_load_lds_dwordx4 v227, s[8:9]
	global_load_lds_dwordx4 v227, s[8:9] offset:1024
	s_add_i32 s0, s0, 2
	s_mov_b32 s1, 0
	s_mov_b32 s6, 1
	s_waitcnt vmcnt(15)
	s_barrier
	v_add_u32_e32 v225, v136, v138
	v_add_u32_e32 v224, v136, v137
	ds_read_b128 v[144:147], v224
	ds_read_b128 v[152:155], v224 offset:1024
	ds_read_b128 v[180:183], v224 offset:2048
	ds_read_b128 v[140:143], v225 offset:8192
	ds_read_b128 v[148:151], v225 offset:9216
	ds_read_b128 v[156:159], v225 offset:10240
	ds_read_b128 v[160:163], v225 offset:11264
	ds_read_b128 v[164:167], v225 offset:12288
	ds_read_b128 v[168:171], v225 offset:13312
	ds_read_b128 v[172:175], v225 offset:14336
	ds_read_b128 v[176:179], v225 offset:15360
	ds_read_b128 v[184:187], v224 offset:3072
	.p2align 6

; template <int N> DI void wait_vm() { asm volatile("s_waitcnt vmcnt(%0)" ::"n"(N) : "memory"); }
; DI void raw_barrier() { asm volatile("" ::: "memory"); __builtin_amdgcn_s_barrier(); asm volatile("" ::: "memory"); }
;     ...
;     auto compute = [&](int cb, bool do_issue, int ikt, int ib) {
;         const char* base = lds + cb * BUF;
;         bf16x8 af[MT], bfr[NT];
; #pragma unroll
;         for (int nt = 0; nt < NT; ++nt) {
;             const int br = BM + (nt / NTS) * (BN / NSEG) + wc * (NTS * 16) + (nt % NTS) * 16;
;             bfr[nt] = *(const bf16x8*)(base + (br + l15) * 64 + rsw);
;         }
; #pragma unroll
;         for (int mt = 0; mt < MT; ++mt) af[mt] = *(const bf16x8*)(base + (wr * WM + mt * 16 + l15) * 64 + rsw);
;     ...
;     for (int kt = 0; kt < KT; ++kt) {
;         if (D > 1 && kt + D - 1 < KT) wait_vm<(D - 1) * NIT>(); else wait_vm<0>();
;         raw_barrier();
.Lpb1_c_entry:
	s_add_i32 s0, s0, 2
	s_mov_b32 s6, 1
	s_waitcnt vmcnt(5)
	s_barrier
	v_add_u32_e32 v225, v136, v138
	v_add_u32_e32 v224, v136, v137
	ds_read_b128 v[144:147], v224
	ds_read_b128 v[152:155], v224 offset:1024
	ds_read_b128 v[180:183], v224 offset:2048
	ds_read_b128 v[140:143], v225 offset:8192
	ds_read_b128 v[148:151], v225 offset:9216
	ds_read_b128 v[156:159], v225 offset:10240
	ds_read_b128 v[160:163], v225 offset:11264
	ds_read_b128 v[164:167], v225 offset:12288
	ds_read_b128 v[168:171], v225 offset:13312
	ds_read_b128 v[172:175], v225 offset:14336
	ds_read_b128 v[176:179], v225 offset:15360
	ds_read_b128 v[184:187], v224 offset:3072
	.p2align 6
